# v19 + DN/WO main epilogue first half: single vmcnt(0) after the 16 residual loads replaced by counted waits at first use (as the compiler already does for the second half)
# speedup vs baseline: 1.0095x; 1.0014x over previous
; __device__ __forceinline__ unsigned pk2(float lo, float hi) { return pg8::cvt_pk_bf16(lo, hi); }
; __device__ __forceinline__ void small_gemm_res(LAS unsigned char* lds, const bf16* A, const bf16* Bt, int K, const float* base_s, float* out, bf16* AB, float* PS, int sm, int sn, int tid_in) {
;     ...
;         const int rl = wr * 32 + m_ * 16 + fr, row = row0 + rl;
;         float ss = 0.f;
; #pragma unroll
;         for (int n = 0; n < 2; ++n) {
;             const int c = col0 + wc * 32 + n * 16 + 4 * fq;
;             const f32x4 y = bv[m_][n] + acc[m_][n];
;             *(f32x4*)(out + (size_t)row * D + c) = y;
;             *(v2u*)(AB + (size_t)row * D + c) = (v2u){pk2(y[0], y[1]), pk2(y[2], y[3])};
.LBB0_221:
	s_mul_i32 s98, s56, 0x120
	v_and_b32_e32 v144, 15, v227
	v_lshrrev_b32_e32 v145, 6, v227
	v_lshl_add_u32 v144, v145, 4, v144
	v_add_u32_e32 v144, s98, v144
	v_add_u32_e32 v144, 0x100, v144
	v_mov_b32_e32 v145, 0
	v_lshl_or_b32 v146, s57, 8, v229
	v_mov_b32_e32 v147, 0
	s_cmp_lt_i32 s56, 56
	s_cselect_b32 s98, s50, s34
	s_cselect_b32 s99, s49, s7
	s_cselect_b32 s100, 0, 0x4000
	v_subrev_u32_e32 v166, s100, v144
	v_mov_b32_e32 v167, 0
	v_lshlrev_b64 v[166:167], 12, v[166:167]
	v_lshl_add_u64 v[166:167], s[98:99], 0, v[166:167]
	v_lshl_add_u64 v[166:167], v[146:147], 2, v[166:167]


; __device__ __forceinline__ float quad_sum(float s) { s += __shfl_xor(s, 16); s += __shfl_xor(s, 32); return s; }
; __device__ __forceinline__ float sq4(const f32x4 a) { return (a[0] * a[0] + a[1] * a[1]) + (a[2] * a[2] + a[3] * a[3]); }
; __device__ __forceinline__ unsigned pk2(float lo, float hi) { return pg8::cvt_pk_bf16(lo, hi); }
;     __device__ __forceinline__ void operator()(const f32x4 (&acc)[2][2][4][2], const Unit& u, int wr, int wc, int fr, int fq) const {
;     ...
;                 const int row = u.pm * BM + ai * HALF + wr * 64 + m * 16 + fr;
;                 const float* bp = (u.pm < 64) ? base_p + (size_t)row * 1024 : base_s + (size_t)(row - E_MP) * 1024;
; #pragma unroll
;                 for (int bj = 0; bj < 2; ++bj) { bv[m][bj][0] = *(const f32x4*)(bp + col0 + bj * HALF); bv[m][bj][1] = *(const f32x4*)(bp + col0 + bj * HALF + 4); }
; __device__ __forceinline__ void small_gemm_res(LAS unsigned char* lds, const bf16* A, const bf16* Bt, int K, const float* base_s, float* out, bf16* AB, float* PS, int sm, int sn, int tid_in) {
;     ...
; #pragma unroll
;     for (int m_ = 0; m_ < 2; ++m_) {
;         const int rl = wr * 32 + m_ * 16 + fr, row = row0 + rl;
;         float ss = 0.f;
; #pragma unroll
;         for (int n = 0; n < 2; ++n) {
;             const int c = col0 + wc * 32 + n * 16 + 4 * fq;
;             const f32x4 y = bv[m_][n] + acc[m_][n];
;             *(f32x4*)(out + (size_t)row * D + c) = y;
;             *(v2u*)(AB + (size_t)row * D + c) = (v2u){pk2(y[0], y[1]), pk2(y[2], y[3])};
;             ss += pg8::sq4(y);
;         }
;         ss = pg8::quad_sum(ss);
;         if (fq == 0) red[rl * 4 + wc] = ss;
;     }
	v_lshlrev_b64 v[148:149], 12, v[144:145]
	v_lshl_add_u64 v[148:149], s[74:75], 0, v[148:149]
	v_lshl_add_u64 v[148:149], v[146:147], 2, v[148:149]
	v_lshlrev_b64 v[150:151], 11, v[144:145]
	v_lshl_add_u64 v[150:151], s[14:15], 0, v[150:151]
	v_lshl_add_u64 v[150:151], v[146:147], 1, v[150:151]
	s_lshl_b32 s98, s57, 4
	s_add_u32 s98, s54, s98
	s_addc_u32 s99, s55, 0
	v_lshlrev_b64 v[164:165], 6, v[144:145]
	v_lshl_add_u64 v[164:165], s[98:99], 0, v[164:165]
	v_xor_b32_e32 v162, 16, v222
	v_lshlrev_b32_e32 v162, 2, v162
	v_xor_b32_e32 v163, 32, v222
	v_lshlrev_b32_e32 v163, 2, v163
	s_waitcnt vmcnt(0)
	v_pk_add_f32 v[128:129], v[236:237], v[128:129]
	v_pk_add_f32 v[130:131], v[238:239], v[130:131]
	v_pk_add_f32 v[132:133], v[240:241], v[132:133]
	v_pk_add_f32 v[134:135], v[242:243], v[134:135]
	v_pk_add_f32 v[136:137], v[244:245], v[136:137]
	v_pk_add_f32 v[138:139], v[246:247], v[138:139]
	v_pk_add_f32 v[140:141], v[200:201], v[140:141]
	v_pk_add_f32 v[142:143], v[202:203], v[142:143]
	global_store_dwordx4 v[148:149], v[128:131], off
	global_store_dwordx4 v[148:149], v[132:135], off offset:16
	global_store_dwordx4 v[148:149], v[136:139], off offset:512
	global_store_dwordx4 v[148:149], v[140:143], off offset:528
	v_cvt_pk_bf16_f32 v152, v128, v129
	v_cvt_pk_bf16_f32 v153, v130, v131
	v_cvt_pk_bf16_f32 v154, v132, v133
	v_cvt_pk_bf16_f32 v155, v134, v135
	v_cvt_pk_bf16_f32 v156, v136, v137
	v_cvt_pk_bf16_f32 v157, v138, v139
	v_cvt_pk_bf16_f32 v158, v140, v141
	v_cvt_pk_bf16_f32 v159, v142, v143
	global_store_dwordx4 v[150:151], v[152:155], off
	global_store_dwordx4 v[150:151], v[156:159], off offset:256
	v_mul_f32_e32 v160, v128, v128
	v_fmac_f32_e32 v160, v129, v129
	v_fmac_f32_e32 v160, v130, v130
	v_fmac_f32_e32 v160, v131, v131
	v_fmac_f32_e32 v160, v132, v132
	v_fmac_f32_e32 v160, v133, v133
	v_fmac_f32_e32 v160, v134, v134
	v_fmac_f32_e32 v160, v135, v135
	v_fmac_f32_e32 v160, v136, v136
	v_fmac_f32_e32 v160, v137, v137
	v_fmac_f32_e32 v160, v138, v138
	v_fmac_f32_e32 v160, v139, v139
	v_fmac_f32_e32 v160, v140, v140
	v_fmac_f32_e32 v160, v141, v141
	v_fmac_f32_e32 v160, v142, v142
	v_fmac_f32_e32 v160, v143, v143
	ds_bpermute_b32 v161, v162, v160
	s_waitcnt lgkmcnt(0)
	v_add_f32_e32 v160, v160, v161
	ds_bpermute_b32 v161, v163, v160
	s_waitcnt lgkmcnt(0)
	v_add_f32_e32 v160, v160, v161
	s_and_saveexec_b64 s[98:99], s[36:37]
	global_store_dword v[164:165], v160, off
	s_or_b64 exec, exec, s[98:99]
	s_lshl_b32 s0, s57, 2
	s_ashr_i32 s1, s0, 31
	s_lshl_b64 s[0:1], s[0:1], 2
	s_add_u32 s40, s54, s0
	s_addc_u32 s41, s55, s1
	s_mul_i32 s98, s56, 0x120
	v_add_u32_e32 v208, s98, v227
	s_cmp_lt_i32 s56, 57
	s_cselect_b64 vcc, -1, 0
	v_add_u32_e32 v128, 0xffffc000, v208
	v_cndmask_b32_e32 v128, v128, v208, vcc
	v_lshl_or_b32 v204, s57, 8, v229
	s_and_b64 s[0:1], vcc, exec
	v_ashrrev_i32_e32 v129, 31, v128
	v_ashrrev_i32_e32 v205, 31, v204
	s_cselect_b32 s43, s49, s7
	s_cselect_b32 s42, s50, s34
	v_lshlrev_b64 v[128:129], 12, v[128:129]
	v_lshl_add_u64 v[128:129], s[42:43], 0, v[128:129]
	v_lshlrev_b64 v[206:207], 2, v[204:205]
	v_lshl_add_u64 v[128:129], v[128:129], 0, v[206:207]
	global_load_dwordx4 v[232:235], v[128:129], off offset:16
	global_load_dwordx4 v[236:239], v[128:129], off
	global_load_dwordx4 v[176:179], v[128:129], off offset:528
	global_load_dwordx4 v[180:183], v[128:129], off offset:512
	v_add_u32_e32 v214, 16, v208
	v_add_u32_e32 v128, 0xffffc010, v208
	v_cndmask_b32_e32 v128, v128, v214, vcc
	v_ashrrev_i32_e32 v129, 31, v128
	v_lshlrev_b64 v[128:129], 12, v[128:129]
	v_lshl_add_u64 v[128:129], s[42:43], 0, v[128:129]
	v_lshl_add_u64 v[128:129], v[128:129], 0, v[206:207]
	global_load_dwordx4 v[168:171], v[128:129], off offset:16
	global_load_dwordx4 v[172:175], v[128:129], off
	global_load_dwordx4 v[160:163], v[128:129], off offset:528
	global_load_dwordx4 v[164:167], v[128:129], off offset:512
	v_add_u32_e32 v212, 32, v208
	v_add_u32_e32 v128, 0xffffc020, v208
	v_cndmask_b32_e32 v128, v128, v212, vcc
	v_ashrrev_i32_e32 v129, 31, v128
	v_lshlrev_b64 v[128:129], 12, v[128:129]
	v_lshl_add_u64 v[128:129], s[42:43], 0, v[128:129]
	v_lshl_add_u64 v[128:129], v[128:129], 0, v[206:207]
	global_load_dwordx4 v[152:155], v[128:129], off offset:16
	global_load_dwordx4 v[156:159], v[128:129], off
	global_load_dwordx4 v[136:139], v[128:129], off offset:528
	global_load_dwordx4 v[140:143], v[128:129], off offset:512
	v_add_u32_e32 v210, 48, v208
	v_add_u32_e32 v128, 0xffffc030, v208
	v_cndmask_b32_e32 v128, v128, v210, vcc
	v_ashrrev_i32_e32 v129, 31, v128
	v_lshlrev_b64 v[128:129], 12, v[128:129]
	v_lshl_add_u64 v[128:129], s[42:43], 0, v[128:129]
	v_lshl_add_u64 v[132:133], v[128:129], 0, v[206:207]
	global_load_dwordx4 v[144:147], v[132:133], off offset:16
	global_load_dwordx4 v[148:151], v[132:133], off
	global_load_dwordx4 v[128:131], v[132:133], off offset:528
	s_nop 0
	global_load_dwordx4 v[132:135], v[132:133], off offset:512
	v_ashrrev_i32_e32 v209, 31, v208
	v_lshlrev_b64 v[224:225], 11, v[208:209]
	v_lshl_add_u64 v[224:225], s[14:15], 0, v[224:225]
	v_lshl_add_u64 v[224:225], v[204:205], 1, v[224:225]

; __device__ __forceinline__ float quad_sum(float s) { s += __shfl_xor(s, 16); s += __shfl_xor(s, 32); return s; }
; __device__ __forceinline__ float sq4(const f32x4 a) { return (a[0] * a[0] + a[1] * a[1]) + (a[2] * a[2] + a[3] * a[3]); }
; __device__ __forceinline__ u32x4 pack8(const f32x4 a, const f32x4 b) { u32x4 w; w.x = cvt_pk_bf16(a[0], a[1]); w.y = cvt_pk_bf16(a[2], a[3]); w.z = cvt_pk_bf16(b[0], b[1]); w.w = cvt_pk_bf16(b[2], b[3]); return w; }
;     __device__ __forceinline__ void operator()(const f32x4 (&acc)[2][2][4][2], const Unit& u, int wr, int wc, int fr, int fq) const {
;     ...
;             for (int m = 0; m < 4; ++m) {
;                 const int row = u.pm * BM + ai * HALF + wr * 64 + m * 16 + fr;
;                 float ss = 0.f;
; #pragma unroll
;                 for (int bj = 0; bj < 2; ++bj) {
;                     const int c = col0 + bj * HALF;
;                     const f32x4 y0 = bv[m][bj][0] + acc[ai][bj][m][0], y1 = bv[m][bj][1] + acc[ai][bj][m][1];
;                     float* d = out + (size_t)row * 1024 + c; *(f32x4*)d = y0; *(f32x4*)(d + 4) = y1;
;                     *(u32x4*)(AB + (size_t)row * 1024 + c) = pack8(y0, y1);
;                     ss += sq4(y0) + sq4(y1);
;                 }
;                 ss = quad_sum(ss);
;                 if (fq == 0) PS[(size_t)row * 16 + u.pn * 4 + wc] = ss;
	s_waitcnt vmcnt(15)
	v_pk_add_f32 v[120:121], v[120:121], v[232:233]
	v_lshlrev_b64 v[232:233], 12, v[208:209]
	v_lshl_add_u64 v[232:233], s[74:75], 0, v[232:233]
	s_waitcnt vmcnt(14)
	v_pk_add_f32 v[126:127], v[126:127], v[238:239]
	v_pk_add_f32 v[124:125], v[124:125], v[236:237]
	v_lshl_add_u64 v[236:237], v[232:233], 0, v[206:207]
	v_pk_add_f32 v[122:123], v[122:123], v[234:235]
	global_store_dwordx4 v[236:237], v[124:127], off
	global_store_dwordx4 v[236:237], v[120:123], off offset:16
	v_cvt_pk_bf16_f32 v232, v124, v125
	v_cvt_pk_bf16_f32 v233, v126, v127
	v_cvt_pk_bf16_f32 v234, v120, v121
	s_waitcnt vmcnt(14)
	v_pk_add_f32 v[118:119], v[118:119], v[182:183]
	v_mul_f32_e32 v125, v125, v125
	v_mul_f32_e32 v121, v121, v121
	v_fmac_f32_e32 v125, v124, v124
	v_mul_f32_e32 v124, v127, v127
	v_fmac_f32_e32 v121, v120, v120
	v_mul_f32_e32 v120, v123, v123
	v_fmac_f32_e32 v124, v126, v126
	v_fmac_f32_e32 v120, v122, v122
	v_add_f32_e32 v124, v125, v124
	v_add_f32_e32 v120, v121, v120
	v_pk_add_f32 v[116:117], v[116:117], v[180:181]
	v_pk_add_f32 v[112:113], v[112:113], v[176:177]
	v_cvt_pk_bf16_f32 v235, v122, v123
	global_store_dwordx4 v[224:225], v[232:235], off
	v_add_f32_e32 v124, v124, v120
	v_pk_add_f32 v[114:115], v[114:115], v[178:179]
	global_store_dwordx4 v[236:237], v[116:119], off offset:512
	global_store_dwordx4 v[236:237], v[112:115], off offset:528
	v_cvt_pk_bf16_f32 v120, v116, v117
	v_cvt_pk_bf16_f32 v121, v118, v119
	v_cvt_pk_bf16_f32 v122, v112, v113
	v_cvt_pk_bf16_f32 v123, v114, v115
	s_nop 0
	v_mul_f32_e32 v117, v117, v117
	v_mul_f32_e32 v113, v113, v113
	v_fmac_f32_e32 v113, v112, v112
	v_mul_f32_e32 v112, v115, v115
	v_fmac_f32_e32 v117, v116, v116
	v_mul_f32_e32 v116, v119, v119
	v_fmac_f32_e32 v112, v114, v114
	v_and_b32_e32 v114, 64, v222
	v_fmac_f32_e32 v116, v118, v118
	v_add_f32_e32 v112, v113, v112
	v_xor_b32_e32 v113, 16, v222
	v_add_u32_e32 v114, 64, v114
	v_add_f32_e32 v116, v117, v116
	v_cmp_lt_i32_e64 s[0:1], v113, v114
	v_add_f32_e32 v112, v116, v112
	v_add_f32_e32 v112, v124, v112
	v_cndmask_b32_e64 v113, v222, v113, s[0:1]
	v_lshlrev_b32_e32 v176, 2, v113
	ds_bpermute_b32 v113, v176, v112
	global_store_dwordx4 v[224:225], v[120:123], off offset:256
	s_waitcnt lgkmcnt(0)
	v_add_f32_e32 v112, v112, v113
	v_xor_b32_e32 v113, 32, v222
	v_cmp_lt_i32_e64 s[0:1], v113, v114
	s_nop 1
	v_cndmask_b32_e64 v113, v222, v113, s[0:1]
	v_lshlrev_b32_e32 v177, 2, v113
	ds_bpermute_b32 v113, v177, v112
	s_and_saveexec_b64 s[0:1], s[36:37]
	v_readlane_b32 s58, v255, 9
	v_readlane_b32 s59, v255, 10
	v_readlane_b32 s92, v255, 11
	v_readlane_b32 s93, v255, 16
	s_cbranch_execz .LBB0_223
	v_lshlrev_b64 v[114:115], 6, v[208:209]
	v_lshl_add_u64 v[114:115], s[40:41], 0, v[114:115]
	s_waitcnt lgkmcnt(0)
	v_add_f32_e32 v112, v112, v113
	global_store_dword v[114:115], v112, off
.LBB0_223:
	s_or_b64 exec, exec, s[0:1]
	v_ashrrev_i32_e32 v215, 31, v214
	s_waitcnt lgkmcnt(0)
	v_lshlrev_b64 v[112:113], 11, v[214:215]
	v_lshl_add_u64 v[116:117], s[14:15], 0, v[112:113]
	v_lshlrev_b64 v[112:113], 12, v[214:215]
	v_lshl_add_u64 v[112:113], s[74:75], 0, v[112:113]
	s_waitcnt vmcnt(16)
	v_pk_add_f32 v[110:111], v[110:111], v[174:175]
	v_pk_add_f32 v[108:109], v[108:109], v[172:173]
	v_pk_add_f32 v[104:105], v[104:105], v[168:169]
	v_lshl_add_u64 v[118:119], v[204:205], 2, v[112:113]
	v_pk_add_f32 v[106:107], v[106:107], v[170:171]
	global_store_dwordx4 v[118:119], v[108:111], off
	global_store_dwordx4 v[118:119], v[104:107], off offset:16
	v_cvt_pk_bf16_f32 v112, v108, v109
	v_cvt_pk_bf16_f32 v113, v110, v111
	v_cvt_pk_bf16_f32 v114, v104, v105
	s_waitcnt vmcnt(16)
	v_pk_add_f32 v[102:103], v[102:103], v[166:167]
	v_mul_f32_e32 v109, v109, v109
	v_mul_f32_e32 v105, v105, v105
	v_fmac_f32_e32 v109, v108, v108
	v_mul_f32_e32 v108, v111, v111
	v_fmac_f32_e32 v105, v104, v104
	v_mul_f32_e32 v104, v107, v107
	v_fmac_f32_e32 v108, v110, v110
	v_fmac_f32_e32 v104, v106, v106
	v_add_f32_e32 v108, v109, v108
	v_add_f32_e32 v104, v105, v104
	v_pk_add_f32 v[100:101], v[100:101], v[164:165]
	v_add_f32_e32 v108, v108, v104
	v_pk_add_f32 v[104:105], v[96:97], v[160:161]
	v_mul_f32_e32 v96, v101, v101
	v_mul_f32_e32 v97, v103, v103
	v_cvt_pk_bf16_f32 v115, v106, v107
	v_pk_add_f32 v[106:107], v[98:99], v[162:163]
	v_fmac_f32_e32 v96, v100, v100
	v_fmac_f32_e32 v97, v102, v102
	v_add_f32_e32 v96, v96, v97
	v_mul_f32_e32 v97, v105, v105
	v_mul_f32_e32 v98, v107, v107
	v_fmac_f32_e32 v97, v104, v104
	v_fmac_f32_e32 v98, v106, v106
	v_add_f32_e32 v97, v97, v98
	v_add_f32_e32 v96, v96, v97
	v_add_f32_e32 v96, v108, v96
	ds_bpermute_b32 v97, v176, v96
	v_lshl_add_u64 v[116:117], v[204:205], 1, v[116:117]
	global_store_dwordx4 v[116:117], v[112:115], off
	global_store_dwordx4 v[118:119], v[100:103], off offset:512
	global_store_dwordx4 v[118:119], v[104:107], off offset:528
	v_cvt_pk_bf16_f32 v98, v100, v101
	v_cvt_pk_bf16_f32 v99, v102, v103
	s_waitcnt lgkmcnt(0)
	v_add_f32_e32 v96, v96, v97
	ds_bpermute_b32 v97, v177, v96
	v_cvt_pk_bf16_f32 v100, v104, v105
	v_cvt_pk_bf16_f32 v101, v106, v107
	global_store_dwordx4 v[116:117], v[98:101], off offset:256
	s_and_saveexec_b64 s[0:1], s[36:37]
	s_cbranch_execz .LBB0_225
	v_lshlrev_b64 v[98:99], 6, v[214:215]
	v_lshl_add_u64 v[98:99], s[40:41], 0, v[98:99]
	s_waitcnt lgkmcnt(0)
	v_add_f32_e32 v96, v96, v97
	global_store_dword v[98:99], v96, off
; __device__ __forceinline__ float quad_sum(float s) { s += __shfl_xor(s, 16); s += __shfl_xor(s, 32); return s; }
; __device__ __forceinline__ float sq4(const f32x4 a) { return (a[0] * a[0] + a[1] * a[1]) + (a[2] * a[2] + a[3] * a[3]); }
; __device__ __forceinline__ u32x4 pack8(const f32x4 a, const f32x4 b) { u32x4 w; w.x = cvt_pk_bf16(a[0], a[1]); w.y = cvt_pk_bf16(a[2], a[3]); w.z = cvt_pk_bf16(b[0], b[1]); w.w = cvt_pk_bf16(b[2], b[3]); return w; }
;     __device__ __forceinline__ void operator()(const f32x4 (&acc)[2][2][4][2], const Unit& u, int wr, int wc, int fr, int fq) const {
;     ...
;             for (int m = 0; m < 4; ++m) {
;                 const int row = u.pm * BM + ai * HALF + wr * 64 + m * 16 + fr;
;                 float ss = 0.f;
; #pragma unroll
;                 for (int bj = 0; bj < 2; ++bj) {
;                     const int c = col0 + bj * HALF;
;                     const f32x4 y0 = bv[m][bj][0] + acc[ai][bj][m][0], y1 = bv[m][bj][1] + acc[ai][bj][m][1];
;                     float* d = out + (size_t)row * 1024 + c; *(f32x4*)d = y0; *(f32x4*)(d + 4) = y1;
;                     *(u32x4*)(AB + (size_t)row * 1024 + c) = pack8(y0, y1);
;                     ss += sq4(y0) + sq4(y1);
;                 }
;                 ss = quad_sum(ss);
;                 if (fq == 0) PS[(size_t)row * 16 + u.pn * 4 + wc] = ss;
.LBB0_225:
	s_or_b64 exec, exec, s[0:1]
	v_ashrrev_i32_e32 v213, 31, v212
	s_waitcnt lgkmcnt(0)
	v_lshlrev_b64 v[96:97], 11, v[212:213]
	v_lshl_add_u64 v[100:101], s[14:15], 0, v[96:97]
	v_lshlrev_b64 v[96:97], 12, v[212:213]
	v_lshl_add_u64 v[96:97], s[74:75], 0, v[96:97]
	s_waitcnt vmcnt(18)
	v_pk_add_f32 v[94:95], v[94:95], v[158:159]
	v_pk_add_f32 v[92:93], v[92:93], v[156:157]
	v_pk_add_f32 v[88:89], v[88:89], v[152:153]
	v_lshl_add_u64 v[102:103], v[204:205], 2, v[96:97]
	v_pk_add_f32 v[90:91], v[90:91], v[154:155]
	global_store_dwordx4 v[102:103], v[92:95], off
	global_store_dwordx4 v[102:103], v[88:91], off offset:16
	v_cvt_pk_bf16_f32 v96, v92, v93
	v_cvt_pk_bf16_f32 v97, v94, v95
	v_cvt_pk_bf16_f32 v98, v88, v89
	s_waitcnt vmcnt(18)
	v_pk_add_f32 v[86:87], v[86:87], v[142:143]
	v_mul_f32_e32 v93, v93, v93
	v_mul_f32_e32 v89, v89, v89
	v_fmac_f32_e32 v93, v92, v92
	v_mul_f32_e32 v92, v95, v95
	v_fmac_f32_e32 v89, v88, v88
	v_mul_f32_e32 v88, v91, v91
	v_fmac_f32_e32 v92, v94, v94
	v_fmac_f32_e32 v88, v90, v90
	v_add_f32_e32 v92, v93, v92
	v_add_f32_e32 v88, v89, v88
	v_pk_add_f32 v[84:85], v[84:85], v[140:141]
	v_add_f32_e32 v92, v92, v88
	v_pk_add_f32 v[88:89], v[80:81], v[136:137]
	v_mul_f32_e32 v80, v85, v85
	v_mul_f32_e32 v81, v87, v87
	v_cvt_pk_bf16_f32 v99, v90, v91
	v_pk_add_f32 v[90:91], v[82:83], v[138:139]
	v_fmac_f32_e32 v80, v84, v84
	v_fmac_f32_e32 v81, v86, v86
	v_add_f32_e32 v80, v80, v81
	v_mul_f32_e32 v81, v89, v89
	v_mul_f32_e32 v82, v91, v91
	v_fmac_f32_e32 v81, v88, v88
	v_fmac_f32_e32 v82, v90, v90
	v_add_f32_e32 v81, v81, v82
	v_add_f32_e32 v80, v80, v81
	v_add_f32_e32 v80, v92, v80
	ds_bpermute_b32 v81, v176, v80
	v_lshl_add_u64 v[100:101], v[204:205], 1, v[100:101]
	global_store_dwordx4 v[100:101], v[96:99], off
	global_store_dwordx4 v[102:103], v[84:87], off offset:512
	global_store_dwordx4 v[102:103], v[88:91], off offset:528
	v_cvt_pk_bf16_f32 v82, v84, v85
	v_cvt_pk_bf16_f32 v83, v86, v87
	s_waitcnt lgkmcnt(0)
	v_add_f32_e32 v80, v80, v81
	ds_bpermute_b32 v81, v177, v80
	v_cvt_pk_bf16_f32 v84, v88, v89
	v_cvt_pk_bf16_f32 v85, v90, v91
	global_store_dwordx4 v[100:101], v[82:85], off offset:256
	s_and_saveexec_b64 s[0:1], s[36:37]
	v_readlane_b32 s94, v255, 12
	v_readlane_b32 s95, v255, 13
	s_cbranch_execz .LBB0_227
	v_lshlrev_b64 v[82:83], 6, v[212:213]
	v_lshl_add_u64 v[82:83], s[40:41], 0, v[82:83]
	s_waitcnt lgkmcnt(0)
	v_add_f32_e32 v80, v80, v81
	global_store_dword v[82:83], v80, off
.LBB0_227:
	s_or_b64 exec, exec, s[0:1]
	v_ashrrev_i32_e32 v211, 31, v210
	s_waitcnt lgkmcnt(0)
	v_lshlrev_b64 v[80:81], 11, v[210:211]
	v_lshl_add_u64 v[84:85], s[14:15], 0, v[80:81]
	v_lshlrev_b64 v[80:81], 12, v[210:211]
	v_lshl_add_u64 v[80:81], s[74:75], 0, v[80:81]
	s_waitcnt vmcnt(20)
	v_pk_add_f32 v[78:79], v[78:79], v[150:151]
	v_pk_add_f32 v[76:77], v[76:77], v[148:149]
	v_pk_add_f32 v[72:73], v[72:73], v[144:145]
	v_lshl_add_u64 v[86:87], v[204:205], 2, v[80:81]
	v_pk_add_f32 v[74:75], v[74:75], v[146:147]
	global_store_dwordx4 v[86:87], v[76:79], off
	global_store_dwordx4 v[86:87], v[72:75], off offset:16
	v_cvt_pk_bf16_f32 v80, v76, v77
	v_cvt_pk_bf16_f32 v81, v78, v79
	v_cvt_pk_bf16_f32 v82, v72, v73
	s_waitcnt vmcnt(20)
	v_pk_add_f32 v[70:71], v[70:71], v[134:135]
	v_mul_f32_e32 v77, v77, v77
	v_mul_f32_e32 v73, v73, v73
	v_fmac_f32_e32 v77, v76, v76
	v_mul_f32_e32 v76, v79, v79
	v_fmac_f32_e32 v73, v72, v72
	v_mul_f32_e32 v72, v75, v75
	v_fmac_f32_e32 v76, v78, v78
	v_fmac_f32_e32 v72, v74, v74
	v_add_f32_e32 v76, v77, v76
	v_add_f32_e32 v72, v73, v72
	v_pk_add_f32 v[68:69], v[68:69], v[132:133]
	v_add_f32_e32 v76, v76, v72
	v_pk_add_f32 v[72:73], v[64:65], v[128:129]
	v_mul_f32_e32 v64, v69, v69
	v_mul_f32_e32 v65, v71, v71
	v_cvt_pk_bf16_f32 v83, v74, v75
	v_pk_add_f32 v[74:75], v[66:67], v[130:131]
	v_fmac_f32_e32 v64, v68, v68
	v_fmac_f32_e32 v65, v70, v70
	v_add_f32_e32 v64, v64, v65
	v_mul_f32_e32 v65, v73, v73
	v_mul_f32_e32 v66, v75, v75
	v_fmac_f32_e32 v65, v72, v72
	v_fmac_f32_e32 v66, v74, v74
	v_add_f32_e32 v65, v65, v66
	v_add_f32_e32 v64, v64, v65
	v_add_f32_e32 v64, v76, v64
	ds_bpermute_b32 v65, v176, v64
	v_lshl_add_u64 v[84:85], v[204:205], 1, v[84:85]
	global_store_dwordx4 v[84:85], v[80:83], off
	global_store_dwordx4 v[86:87], v[68:71], off offset:512
	global_store_dwordx4 v[86:87], v[72:75], off offset:528
	v_cvt_pk_bf16_f32 v66, v68, v69
	v_cvt_pk_bf16_f32 v67, v70, v71
	s_waitcnt lgkmcnt(0)
	v_add_f32_e32 v64, v64, v65
	ds_bpermute_b32 v65, v177, v64
	v_cvt_pk_bf16_f32 v68, v72, v73
	v_cvt_pk_bf16_f32 v69, v74, v75
	global_store_dwordx4 v[84:85], v[66:69], off offset:256
	s_and_saveexec_b64 s[0:1], s[36:37]
	s_cbranch_execz .LBB0_229
	v_lshlrev_b64 v[66:67], 6, v[210:211]
	v_lshl_add_u64 v[66:67], s[40:41], 0, v[66:67]
	s_waitcnt lgkmcnt(0)
	v_add_f32_e32 v64, v64, v65
	global_store_dword v[66:67], v64, off

; __device__ __forceinline__ unsigned pk2(float lo, float hi) { return pg8::cvt_pk_bf16(lo, hi); }
; __device__ __forceinline__ void small_gemm_res(LAS unsigned char* lds, const bf16* A, const bf16* Bt, int K, const float* base_s, float* out, bf16* AB, float* PS, int sm, int sn, int tid_in) {
;     ...
;         const int rl = wr * 32 + m_ * 16 + fr, row = row0 + rl;
;         float ss = 0.f;
; #pragma unroll
;         for (int n = 0; n < 2; ++n) {
;             const int c = col0 + wc * 32 + n * 16 + 4 * fq;
;             const f32x4 y = bv[m_][n] + acc[m_][n];
;             *(f32x4*)(out + (size_t)row * D + c) = y;
;             *(v2u*)(AB + (size_t)row * D + c) = (v2u){pk2(y[0], y[1]), pk2(y[2], y[3])};
.LBB0_464:
	s_mul_i32 s98, s48, 0x120
	v_and_b32_e32 v144, 15, v227
	v_lshrrev_b32_e32 v145, 6, v227
	v_lshl_add_u32 v144, v145, 4, v144
	v_add_u32_e32 v144, s98, v144
	v_add_u32_e32 v144, 0x100, v144
	v_mov_b32_e32 v145, 0
	v_lshl_or_b32 v146, s49, 8, v229
	v_mov_b32_e32 v147, 0
	v_lshlrev_b64 v[148:149], 12, v[144:145]
	v_lshl_add_u64 v[148:149], s[74:75], 0, v[148:149]
	v_lshl_add_u64 v[148:149], v[146:147], 2, v[148:149]


; __device__ __forceinline__ float quad_sum(float s) { s += __shfl_xor(s, 16); s += __shfl_xor(s, 32); return s; }
; __device__ __forceinline__ float sq4(const f32x4 a) { return (a[0] * a[0] + a[1] * a[1]) + (a[2] * a[2] + a[3] * a[3]); }
; __device__ __forceinline__ unsigned pk2(float lo, float hi) { return pg8::cvt_pk_bf16(lo, hi); }
;     __device__ __forceinline__ void operator()(const f32x4 (&acc)[2][2][4][2], const Unit& u, int wr, int wc, int fr, int fq) const {
;     ...
;                 const int row = u.pm * BM + ai * HALF + wr * 64 + m * 16 + fr;
;                 const float* bp = (u.pm < 64) ? base_p + (size_t)row * 1024 : base_s + (size_t)(row - E_MP) * 1024;
; #pragma unroll
;                 for (int bj = 0; bj < 2; ++bj) { bv[m][bj][0] = *(const f32x4*)(bp + col0 + bj * HALF); bv[m][bj][1] = *(const f32x4*)(bp + col0 + bj * HALF + 4); }
; __device__ __forceinline__ void small_gemm_res(LAS unsigned char* lds, const bf16* A, const bf16* Bt, int K, const float* base_s, float* out, bf16* AB, float* PS, int sm, int sn, int tid_in) {
;     ...
; #pragma unroll
;     for (int m_ = 0; m_ < 2; ++m_) {
;         const int rl = wr * 32 + m_ * 16 + fr, row = row0 + rl;
;         float ss = 0.f;
; #pragma unroll
;         for (int n = 0; n < 2; ++n) {
;             const int c = col0 + wc * 32 + n * 16 + 4 * fq;
;             const f32x4 y = bv[m_][n] + acc[m_][n];
;             *(f32x4*)(out + (size_t)row * D + c) = y;
;             *(v2u*)(AB + (size_t)row * D + c) = (v2u){pk2(y[0], y[1]), pk2(y[2], y[3])};
;             ss += pg8::sq4(y);
;         }
;         ss = pg8::quad_sum(ss);
;         if (fq == 0) red[rl * 4 + wc] = ss;
;     }
	v_lshlrev_b64 v[150:151], 11, v[144:145]
	v_lshl_add_u64 v[150:151], s[12:13], 0, v[150:151]
	v_lshl_add_u64 v[150:151], v[146:147], 1, v[150:151]
	s_lshl_b32 s98, s49, 4
	s_add_u32 s98, s44, s98
	s_addc_u32 s99, s45, 0
	v_lshlrev_b64 v[164:165], 6, v[144:145]
	v_lshl_add_u64 v[164:165], s[98:99], 0, v[164:165]
	v_xor_b32_e32 v162, 16, v222
	v_lshlrev_b32_e32 v162, 2, v162
	v_xor_b32_e32 v163, 32, v222
	v_lshlrev_b32_e32 v163, 2, v163
	s_waitcnt vmcnt(0)
	v_pk_add_f32 v[128:129], v[236:237], v[128:129]
	v_pk_add_f32 v[130:131], v[238:239], v[130:131]
	v_pk_add_f32 v[132:133], v[240:241], v[132:133]
	v_pk_add_f32 v[134:135], v[242:243], v[134:135]
	v_pk_add_f32 v[136:137], v[244:245], v[136:137]
	v_pk_add_f32 v[138:139], v[246:247], v[138:139]
	v_pk_add_f32 v[140:141], v[200:201], v[140:141]
	v_pk_add_f32 v[142:143], v[202:203], v[142:143]
	global_store_dwordx4 v[148:149], v[128:131], off
	global_store_dwordx4 v[148:149], v[132:135], off offset:16
	global_store_dwordx4 v[148:149], v[136:139], off offset:512
	global_store_dwordx4 v[148:149], v[140:143], off offset:528
	v_cvt_pk_bf16_f32 v152, v128, v129
	v_cvt_pk_bf16_f32 v153, v130, v131
	v_cvt_pk_bf16_f32 v154, v132, v133
	v_cvt_pk_bf16_f32 v155, v134, v135
	v_cvt_pk_bf16_f32 v156, v136, v137
	v_cvt_pk_bf16_f32 v157, v138, v139
	v_cvt_pk_bf16_f32 v158, v140, v141
	v_cvt_pk_bf16_f32 v159, v142, v143
	global_store_dwordx4 v[150:151], v[152:155], off
	global_store_dwordx4 v[150:151], v[156:159], off offset:256
	v_mul_f32_e32 v160, v128, v128
	v_fmac_f32_e32 v160, v129, v129
	v_fmac_f32_e32 v160, v130, v130
	v_fmac_f32_e32 v160, v131, v131
	v_fmac_f32_e32 v160, v132, v132
	v_fmac_f32_e32 v160, v133, v133
	v_fmac_f32_e32 v160, v134, v134
	v_fmac_f32_e32 v160, v135, v135
	v_fmac_f32_e32 v160, v136, v136
	v_fmac_f32_e32 v160, v137, v137
	v_fmac_f32_e32 v160, v138, v138
	v_fmac_f32_e32 v160, v139, v139
	v_fmac_f32_e32 v160, v140, v140
	v_fmac_f32_e32 v160, v141, v141
	v_fmac_f32_e32 v160, v142, v142
	v_fmac_f32_e32 v160, v143, v143
	ds_bpermute_b32 v161, v162, v160
	s_waitcnt lgkmcnt(0)
	v_add_f32_e32 v160, v160, v161
	ds_bpermute_b32 v161, v163, v160
	s_waitcnt lgkmcnt(0)
	v_add_f32_e32 v160, v160, v161
	s_and_saveexec_b64 s[98:99], s[36:37]
	global_store_dword v[164:165], v160, off
	s_or_b64 exec, exec, s[98:99]
	s_lshl_b32 s0, s49, 2
	s_ashr_i32 s1, s0, 31
	s_lshl_b64 s[0:1], s[0:1], 2
	s_add_u32 s22, s44, s0
	s_addc_u32 s23, s45, s1
	s_mul_i32 s98, s48, 0x120
	v_add_u32_e32 v208, s98, v227
	s_cmp_eq_u32 s48, s48
	s_cselect_b64 vcc, -1, 0
	v_add_u32_e32 v128, 0xffffc000, v208
	v_cndmask_b32_e32 v128, v128, v208, vcc
	v_lshl_or_b32 v204, s49, 8, v229
	s_and_b64 s[0:1], vcc, exec
	v_ashrrev_i32_e32 v129, 31, v128
	v_ashrrev_i32_e32 v205, 31, v204
	s_cselect_b32 s25, s75, s57
	s_cselect_b32 s24, s74, s56
	v_lshlrev_b64 v[128:129], 12, v[128:129]
	v_lshl_add_u64 v[128:129], s[24:25], 0, v[128:129]
	v_lshlrev_b64 v[206:207], 2, v[204:205]
	v_lshl_add_u64 v[128:129], v[128:129], 0, v[206:207]
	global_load_dwordx4 v[232:235], v[128:129], off offset:16
	global_load_dwordx4 v[236:239], v[128:129], off
	global_load_dwordx4 v[176:179], v[128:129], off offset:528
	global_load_dwordx4 v[180:183], v[128:129], off offset:512
	v_add_u32_e32 v214, 16, v208
	v_add_u32_e32 v128, 0xffffc010, v208
	v_cndmask_b32_e32 v128, v128, v214, vcc
	v_ashrrev_i32_e32 v129, 31, v128
	v_lshlrev_b64 v[128:129], 12, v[128:129]
	v_lshl_add_u64 v[128:129], s[24:25], 0, v[128:129]
	v_lshl_add_u64 v[128:129], v[128:129], 0, v[206:207]
	global_load_dwordx4 v[168:171], v[128:129], off offset:16
	global_load_dwordx4 v[172:175], v[128:129], off
	global_load_dwordx4 v[160:163], v[128:129], off offset:528
	global_load_dwordx4 v[164:167], v[128:129], off offset:512
	v_add_u32_e32 v212, 32, v208
	v_add_u32_e32 v128, 0xffffc020, v208
	v_cndmask_b32_e32 v128, v128, v212, vcc
	v_ashrrev_i32_e32 v129, 31, v128
	v_lshlrev_b64 v[128:129], 12, v[128:129]
	v_lshl_add_u64 v[128:129], s[24:25], 0, v[128:129]
	v_lshl_add_u64 v[128:129], v[128:129], 0, v[206:207]
	global_load_dwordx4 v[152:155], v[128:129], off offset:16
	global_load_dwordx4 v[156:159], v[128:129], off
	global_load_dwordx4 v[136:139], v[128:129], off offset:528
	global_load_dwordx4 v[140:143], v[128:129], off offset:512
	v_add_u32_e32 v210, 48, v208
	v_add_u32_e32 v128, 0xffffc030, v208
	v_cndmask_b32_e32 v128, v128, v210, vcc
	v_ashrrev_i32_e32 v129, 31, v128
	v_lshlrev_b64 v[128:129], 12, v[128:129]
	v_lshl_add_u64 v[128:129], s[24:25], 0, v[128:129]
	v_lshl_add_u64 v[132:133], v[128:129], 0, v[206:207]
	global_load_dwordx4 v[144:147], v[132:133], off offset:16
	global_load_dwordx4 v[148:151], v[132:133], off
	global_load_dwordx4 v[128:131], v[132:133], off offset:528
	s_nop 0
	global_load_dwordx4 v[132:135], v[132:133], off offset:512
	v_ashrrev_i32_e32 v209, 31, v208
	v_lshlrev_b64 v[224:225], 11, v[208:209]
	v_lshl_add_u64 v[224:225], s[12:13], 0, v[224:225]
	v_lshl_add_u64 v[224:225], v[204:205], 1, v[224:225]

; __device__ __forceinline__ float quad_sum(float s) { s += __shfl_xor(s, 16); s += __shfl_xor(s, 32); return s; }
; __device__ __forceinline__ float sq4(const f32x4 a) { return (a[0] * a[0] + a[1] * a[1]) + (a[2] * a[2] + a[3] * a[3]); }
; __device__ __forceinline__ u32x4 pack8(const f32x4 a, const f32x4 b) { u32x4 w; w.x = cvt_pk_bf16(a[0], a[1]); w.y = cvt_pk_bf16(a[2], a[3]); w.z = cvt_pk_bf16(b[0], b[1]); w.w = cvt_pk_bf16(b[2], b[3]); return w; }
;     __device__ __forceinline__ void operator()(const f32x4 (&acc)[2][2][4][2], const Unit& u, int wr, int wc, int fr, int fq) const {
;     ...
;             for (int m = 0; m < 4; ++m) {
;                 const int row = u.pm * BM + ai * HALF + wr * 64 + m * 16 + fr;
;                 float ss = 0.f;
; #pragma unroll
;                 for (int bj = 0; bj < 2; ++bj) {
;                     const int c = col0 + bj * HALF;
;                     const f32x4 y0 = bv[m][bj][0] + acc[ai][bj][m][0], y1 = bv[m][bj][1] + acc[ai][bj][m][1];
;                     float* d = out + (size_t)row * 1024 + c; *(f32x4*)d = y0; *(f32x4*)(d + 4) = y1;
;                     *(u32x4*)(AB + (size_t)row * 1024 + c) = pack8(y0, y1);
;                     ss += sq4(y0) + sq4(y1);
;                 }
;                 ss = quad_sum(ss);
;                 if (fq == 0) PS[(size_t)row * 16 + u.pn * 4 + wc] = ss;
	s_waitcnt vmcnt(15)
	v_pk_add_f32 v[120:121], v[120:121], v[232:233]
	v_lshlrev_b64 v[232:233], 12, v[208:209]
	v_lshl_add_u64 v[232:233], s[74:75], 0, v[232:233]
	s_waitcnt vmcnt(14)
	v_pk_add_f32 v[126:127], v[126:127], v[238:239]
	v_pk_add_f32 v[124:125], v[124:125], v[236:237]
	v_lshl_add_u64 v[236:237], v[232:233], 0, v[206:207]
	v_pk_add_f32 v[122:123], v[122:123], v[234:235]
	global_store_dwordx4 v[236:237], v[124:127], off
	global_store_dwordx4 v[236:237], v[120:123], off offset:16
	v_cvt_pk_bf16_f32 v232, v124, v125
	v_cvt_pk_bf16_f32 v233, v126, v127
	v_cvt_pk_bf16_f32 v234, v120, v121
	s_waitcnt vmcnt(14)
	v_pk_add_f32 v[118:119], v[118:119], v[182:183]
	v_mul_f32_e32 v125, v125, v125
	v_mul_f32_e32 v121, v121, v121
	v_fmac_f32_e32 v125, v124, v124
	v_mul_f32_e32 v124, v127, v127
	v_fmac_f32_e32 v121, v120, v120
	v_mul_f32_e32 v120, v123, v123
	v_fmac_f32_e32 v124, v126, v126
	v_fmac_f32_e32 v120, v122, v122
	v_add_f32_e32 v124, v125, v124
	v_add_f32_e32 v120, v121, v120
	v_pk_add_f32 v[116:117], v[116:117], v[180:181]
	v_pk_add_f32 v[112:113], v[112:113], v[176:177]
	v_cvt_pk_bf16_f32 v235, v122, v123
	global_store_dwordx4 v[224:225], v[232:235], off
	v_add_f32_e32 v124, v124, v120
	v_pk_add_f32 v[114:115], v[114:115], v[178:179]
	global_store_dwordx4 v[236:237], v[116:119], off offset:512
	global_store_dwordx4 v[236:237], v[112:115], off offset:528
	v_cvt_pk_bf16_f32 v120, v116, v117
	v_cvt_pk_bf16_f32 v121, v118, v119
	v_cvt_pk_bf16_f32 v122, v112, v113
	v_cvt_pk_bf16_f32 v123, v114, v115
	s_nop 0
	v_mul_f32_e32 v117, v117, v117
	v_mul_f32_e32 v113, v113, v113
	v_fmac_f32_e32 v113, v112, v112
	v_mul_f32_e32 v112, v115, v115
	v_fmac_f32_e32 v117, v116, v116
	v_mul_f32_e32 v116, v119, v119
	v_fmac_f32_e32 v112, v114, v114
	v_and_b32_e32 v114, 64, v222
	v_fmac_f32_e32 v116, v118, v118
	v_add_f32_e32 v112, v113, v112
	v_xor_b32_e32 v113, 16, v222
	v_add_u32_e32 v114, 64, v114
	v_add_f32_e32 v116, v117, v116
	v_cmp_lt_i32_e64 s[0:1], v113, v114
	v_add_f32_e32 v112, v116, v112
	v_add_f32_e32 v112, v124, v112
	v_cndmask_b32_e64 v113, v222, v113, s[0:1]
	v_lshlrev_b32_e32 v176, 2, v113
	ds_bpermute_b32 v113, v176, v112
	global_store_dwordx4 v[224:225], v[120:123], off offset:256
	s_waitcnt lgkmcnt(0)
	v_add_f32_e32 v112, v112, v113
	v_xor_b32_e32 v113, 32, v222
	v_cmp_lt_i32_e64 s[0:1], v113, v114
	s_nop 1
	v_cndmask_b32_e64 v113, v222, v113, s[0:1]
	v_lshlrev_b32_e32 v177, 2, v113
	ds_bpermute_b32 v113, v177, v112
	s_and_saveexec_b64 s[0:1], s[36:37]
	s_cbranch_execz .LBB0_466
	v_lshlrev_b64 v[114:115], 6, v[208:209]
	v_lshl_add_u64 v[114:115], s[22:23], 0, v[114:115]
	s_waitcnt lgkmcnt(0)
	v_add_f32_e32 v112, v112, v113
	global_store_dword v[114:115], v112, off
.LBB0_466:
	s_or_b64 exec, exec, s[0:1]
	v_ashrrev_i32_e32 v215, 31, v214
	s_waitcnt lgkmcnt(0)
	v_lshlrev_b64 v[112:113], 11, v[214:215]
	v_lshl_add_u64 v[116:117], s[12:13], 0, v[112:113]
	v_lshlrev_b64 v[112:113], 12, v[214:215]
	v_lshl_add_u64 v[112:113], s[74:75], 0, v[112:113]
	s_waitcnt vmcnt(16)
	v_pk_add_f32 v[110:111], v[110:111], v[174:175]
	v_pk_add_f32 v[108:109], v[108:109], v[172:173]
	v_pk_add_f32 v[104:105], v[104:105], v[168:169]
	v_lshl_add_u64 v[118:119], v[204:205], 2, v[112:113]
	v_pk_add_f32 v[106:107], v[106:107], v[170:171]
	global_store_dwordx4 v[118:119], v[108:111], off
	global_store_dwordx4 v[118:119], v[104:107], off offset:16
	v_cvt_pk_bf16_f32 v112, v108, v109
	v_cvt_pk_bf16_f32 v113, v110, v111
	v_cvt_pk_bf16_f32 v114, v104, v105
	s_waitcnt vmcnt(16)
	v_pk_add_f32 v[102:103], v[102:103], v[166:167]
	v_mul_f32_e32 v109, v109, v109
	v_mul_f32_e32 v105, v105, v105
	v_fmac_f32_e32 v109, v108, v108
	v_mul_f32_e32 v108, v111, v111
	v_fmac_f32_e32 v105, v104, v104
	v_mul_f32_e32 v104, v107, v107
	v_fmac_f32_e32 v108, v110, v110
	v_fmac_f32_e32 v104, v106, v106
	v_add_f32_e32 v108, v109, v108
	v_add_f32_e32 v104, v105, v104
	v_pk_add_f32 v[100:101], v[100:101], v[164:165]
	v_add_f32_e32 v108, v108, v104
	v_pk_add_f32 v[104:105], v[96:97], v[160:161]
	v_mul_f32_e32 v96, v101, v101
	v_mul_f32_e32 v97, v103, v103
	v_cvt_pk_bf16_f32 v115, v106, v107
	v_pk_add_f32 v[106:107], v[98:99], v[162:163]
	v_fmac_f32_e32 v96, v100, v100
	v_fmac_f32_e32 v97, v102, v102
	v_add_f32_e32 v96, v96, v97
	v_mul_f32_e32 v97, v105, v105
	v_mul_f32_e32 v98, v107, v107
	v_fmac_f32_e32 v97, v104, v104
	v_fmac_f32_e32 v98, v106, v106
	v_add_f32_e32 v97, v97, v98
	v_add_f32_e32 v96, v96, v97
	v_add_f32_e32 v96, v108, v96
	ds_bpermute_b32 v97, v176, v96
	v_lshl_add_u64 v[116:117], v[204:205], 1, v[116:117]
	global_store_dwordx4 v[116:117], v[112:115], off
	global_store_dwordx4 v[118:119], v[100:103], off offset:512
	global_store_dwordx4 v[118:119], v[104:107], off offset:528
	v_cvt_pk_bf16_f32 v98, v100, v101
	v_cvt_pk_bf16_f32 v99, v102, v103
	s_waitcnt lgkmcnt(0)
	v_add_f32_e32 v96, v96, v97
	ds_bpermute_b32 v97, v177, v96
	v_cvt_pk_bf16_f32 v100, v104, v105
	v_cvt_pk_bf16_f32 v101, v106, v107
	global_store_dwordx4 v[116:117], v[98:101], off offset:256
	s_and_saveexec_b64 s[0:1], s[36:37]
	s_cbranch_execz .LBB0_468
	v_lshlrev_b64 v[98:99], 6, v[214:215]
	v_lshl_add_u64 v[98:99], s[22:23], 0, v[98:99]
	s_waitcnt lgkmcnt(0)
	v_add_f32_e32 v96, v96, v97
	global_store_dword v[98:99], v96, off
; __device__ __forceinline__ float quad_sum(float s) { s += __shfl_xor(s, 16); s += __shfl_xor(s, 32); return s; }
; __device__ __forceinline__ float sq4(const f32x4 a) { return (a[0] * a[0] + a[1] * a[1]) + (a[2] * a[2] + a[3] * a[3]); }
; __device__ __forceinline__ u32x4 pack8(const f32x4 a, const f32x4 b) { u32x4 w; w.x = cvt_pk_bf16(a[0], a[1]); w.y = cvt_pk_bf16(a[2], a[3]); w.z = cvt_pk_bf16(b[0], b[1]); w.w = cvt_pk_bf16(b[2], b[3]); return w; }
;     __device__ __forceinline__ void operator()(const f32x4 (&acc)[2][2][4][2], const Unit& u, int wr, int wc, int fr, int fq) const {
;     ...
;             for (int m = 0; m < 4; ++m) {
;                 const int row = u.pm * BM + ai * HALF + wr * 64 + m * 16 + fr;
;                 float ss = 0.f;
; #pragma unroll
;                 for (int bj = 0; bj < 2; ++bj) {
;                     const int c = col0 + bj * HALF;
;                     const f32x4 y0 = bv[m][bj][0] + acc[ai][bj][m][0], y1 = bv[m][bj][1] + acc[ai][bj][m][1];
;                     float* d = out + (size_t)row * 1024 + c; *(f32x4*)d = y0; *(f32x4*)(d + 4) = y1;
;                     *(u32x4*)(AB + (size_t)row * 1024 + c) = pack8(y0, y1);
;                     ss += sq4(y0) + sq4(y1);
;                 }
;                 ss = quad_sum(ss);
;                 if (fq == 0) PS[(size_t)row * 16 + u.pn * 4 + wc] = ss;
.LBB0_468:
	s_or_b64 exec, exec, s[0:1]
	v_ashrrev_i32_e32 v213, 31, v212
	s_waitcnt lgkmcnt(0)
	v_lshlrev_b64 v[96:97], 11, v[212:213]
	v_lshl_add_u64 v[100:101], s[12:13], 0, v[96:97]
	v_lshlrev_b64 v[96:97], 12, v[212:213]
	v_lshl_add_u64 v[96:97], s[74:75], 0, v[96:97]
	s_waitcnt vmcnt(18)
	v_pk_add_f32 v[94:95], v[94:95], v[158:159]
	v_pk_add_f32 v[92:93], v[92:93], v[156:157]
	v_pk_add_f32 v[88:89], v[88:89], v[152:153]
	v_lshl_add_u64 v[102:103], v[204:205], 2, v[96:97]
	v_pk_add_f32 v[90:91], v[90:91], v[154:155]
	global_store_dwordx4 v[102:103], v[92:95], off
	global_store_dwordx4 v[102:103], v[88:91], off offset:16
	v_cvt_pk_bf16_f32 v96, v92, v93
	v_cvt_pk_bf16_f32 v97, v94, v95
	v_cvt_pk_bf16_f32 v98, v88, v89
	s_waitcnt vmcnt(18)
	v_pk_add_f32 v[86:87], v[86:87], v[142:143]
	v_mul_f32_e32 v93, v93, v93
	v_mul_f32_e32 v89, v89, v89
	v_fmac_f32_e32 v93, v92, v92
	v_mul_f32_e32 v92, v95, v95
	v_fmac_f32_e32 v89, v88, v88
	v_mul_f32_e32 v88, v91, v91
	v_fmac_f32_e32 v92, v94, v94
	v_fmac_f32_e32 v88, v90, v90
	v_add_f32_e32 v92, v93, v92
	v_add_f32_e32 v88, v89, v88
	v_pk_add_f32 v[84:85], v[84:85], v[140:141]
	v_add_f32_e32 v92, v92, v88
	v_pk_add_f32 v[88:89], v[80:81], v[136:137]
	v_mul_f32_e32 v80, v85, v85
	v_mul_f32_e32 v81, v87, v87
	v_cvt_pk_bf16_f32 v99, v90, v91
	v_pk_add_f32 v[90:91], v[82:83], v[138:139]
	v_fmac_f32_e32 v80, v84, v84
	v_fmac_f32_e32 v81, v86, v86
	v_add_f32_e32 v80, v80, v81
	v_mul_f32_e32 v81, v89, v89
	v_mul_f32_e32 v82, v91, v91
	v_fmac_f32_e32 v81, v88, v88
	v_fmac_f32_e32 v82, v90, v90
	v_add_f32_e32 v81, v81, v82
	v_add_f32_e32 v80, v80, v81
	v_add_f32_e32 v80, v92, v80
	ds_bpermute_b32 v81, v176, v80
	v_lshl_add_u64 v[100:101], v[204:205], 1, v[100:101]
	global_store_dwordx4 v[100:101], v[96:99], off
	global_store_dwordx4 v[102:103], v[84:87], off offset:512
	global_store_dwordx4 v[102:103], v[88:91], off offset:528
	v_cvt_pk_bf16_f32 v82, v84, v85
	v_cvt_pk_bf16_f32 v83, v86, v87
	s_waitcnt lgkmcnt(0)
	v_add_f32_e32 v80, v80, v81
	ds_bpermute_b32 v81, v177, v80
	v_cvt_pk_bf16_f32 v84, v88, v89
	v_cvt_pk_bf16_f32 v85, v90, v91
	global_store_dwordx4 v[100:101], v[82:85], off offset:256
	s_and_saveexec_b64 s[0:1], s[36:37]
	s_cbranch_execz .LBB0_470
	v_lshlrev_b64 v[82:83], 6, v[212:213]
	v_lshl_add_u64 v[82:83], s[22:23], 0, v[82:83]
	s_waitcnt lgkmcnt(0)
	v_add_f32_e32 v80, v80, v81
	global_store_dword v[82:83], v80, off
.LBB0_470:
	s_or_b64 exec, exec, s[0:1]
	v_ashrrev_i32_e32 v211, 31, v210
	s_waitcnt lgkmcnt(0)
	v_lshlrev_b64 v[80:81], 11, v[210:211]
	v_lshl_add_u64 v[84:85], s[12:13], 0, v[80:81]
	v_lshlrev_b64 v[80:81], 12, v[210:211]
	v_lshl_add_u64 v[80:81], s[74:75], 0, v[80:81]
	s_waitcnt vmcnt(20)
	v_pk_add_f32 v[78:79], v[78:79], v[150:151]
	v_pk_add_f32 v[76:77], v[76:77], v[148:149]
	v_pk_add_f32 v[72:73], v[72:73], v[144:145]
	v_lshl_add_u64 v[86:87], v[204:205], 2, v[80:81]
	v_pk_add_f32 v[74:75], v[74:75], v[146:147]
	global_store_dwordx4 v[86:87], v[76:79], off
	global_store_dwordx4 v[86:87], v[72:75], off offset:16
	v_cvt_pk_bf16_f32 v80, v76, v77
	v_cvt_pk_bf16_f32 v81, v78, v79
	v_cvt_pk_bf16_f32 v82, v72, v73
	s_waitcnt vmcnt(20)
	v_pk_add_f32 v[70:71], v[70:71], v[134:135]
	v_mul_f32_e32 v77, v77, v77
	v_mul_f32_e32 v73, v73, v73
	v_fmac_f32_e32 v77, v76, v76
	v_mul_f32_e32 v76, v79, v79
	v_fmac_f32_e32 v73, v72, v72
	v_mul_f32_e32 v72, v75, v75
	v_fmac_f32_e32 v76, v78, v78
	v_fmac_f32_e32 v72, v74, v74
	v_add_f32_e32 v76, v77, v76
	v_add_f32_e32 v72, v73, v72
	v_pk_add_f32 v[68:69], v[68:69], v[132:133]
	v_add_f32_e32 v76, v76, v72
	v_pk_add_f32 v[72:73], v[64:65], v[128:129]
	v_mul_f32_e32 v64, v69, v69
	v_mul_f32_e32 v65, v71, v71
	v_cvt_pk_bf16_f32 v83, v74, v75
	v_pk_add_f32 v[74:75], v[66:67], v[130:131]
	v_fmac_f32_e32 v64, v68, v68
	v_fmac_f32_e32 v65, v70, v70
	v_add_f32_e32 v64, v64, v65
	v_mul_f32_e32 v65, v73, v73
	v_mul_f32_e32 v66, v75, v75
	v_fmac_f32_e32 v65, v72, v72
	v_fmac_f32_e32 v66, v74, v74
	v_add_f32_e32 v65, v65, v66
	v_add_f32_e32 v64, v64, v65
	v_add_f32_e32 v64, v76, v64
	ds_bpermute_b32 v65, v176, v64
	v_lshl_add_u64 v[84:85], v[204:205], 1, v[84:85]
	global_store_dwordx4 v[84:85], v[80:83], off
	global_store_dwordx4 v[86:87], v[68:71], off offset:512
	global_store_dwordx4 v[86:87], v[72:75], off offset:528
	v_cvt_pk_bf16_f32 v66, v68, v69
	v_cvt_pk_bf16_f32 v67, v70, v71
	s_waitcnt lgkmcnt(0)
	v_add_f32_e32 v64, v64, v65
	ds_bpermute_b32 v65, v177, v64
	v_cvt_pk_bf16_f32 v68, v72, v73
	v_cvt_pk_bf16_f32 v69, v74, v75
	global_store_dwordx4 v[84:85], v[66:69], off offset:256
	s_and_saveexec_b64 s[0:1], s[36:37]
	s_cbranch_execz .LBB0_472
	v_lshlrev_b64 v[66:67], 6, v[210:211]
	v_lshl_add_u64 v[66:67], s[22:23], 0, v[66:67]
	s_waitcnt lgkmcnt(0)
	v_add_f32_e32 v64, v64, v65
	global_store_dword v[66:67], v64, off
